# GEMM phases: one static priority raise for the wave group that runs one barrier behind
# baseline (speedup 1.0000x reference)
; DI int get_tid() { int t = threadIdx.x; asm volatile("" : "+v"(t)); return t; }
; #define PG8_STAGE(bufoff, gbase, voff) do { _Pragma("unroll") for (int _i = 0; _i < 2; ++_i) \
;     __builtin_amdgcn_global_load_lds((const unsigned*)((const char*)(gbase) + (voff)[_i]), (LAS unsigned*)(lds + (bufoff) + ldsw + _i * 8192), 16, 0, 0); } while (0)
; #define PG8_BAR __builtin_amdgcn_s_barrier()
; template <class Epi, class Sched>
; DI void gemm_phase(LAS unsigned char* lds, const Gemm g, const Sched& S, const Epi& E) {
;   const int tid = get_tid(), wid = __builtin_amdgcn_readfirstlane(tid >> 6), lane = tid & 63, wr = wid >> 2, wc = wid & 3, fr = lane & 15, fq = lane >> 4;
;   const int K = g.K, nt = K / BK;
;   unsigned voffA[2], voffB[2];
; #pragma unroll
;   for (int i = 0; i < 2; ++i) { int R, C; stage_rc(tid * 16 + i * 8192, R, C); const int Rb = Epi::PERM ? ((R & ~31) + perm32(R & 31)) : R;
;     voffA[i] = (unsigned)(R * K + C) * 2u; voffB[i] = (unsigned)(Rb * K + C) * 2u; }
;   const size_t kstep = (size_t)(BK * 2);
;   const size_t hstep = (size_t)HALF * K * 2;
;   const size_t tstep = 2 * hstep;
;   const unsigned ldsw = (unsigned)wid * 1024u;
;   const int aoff = lds_byte(wr * 64 + fr, fq * 8), boff = lds_byte(wc * 32 + fr, fq * 8);
;     ...
;   Unit cur, nxt; int ui = 0;
;   if (!S.next(0, cur)) return;
;   f32x4 acc[2][2][4][2];
; #pragma unroll
;   for (int a = 0; a < 2; ++a)
; #pragma unroll
;     for (int b = 0; b < 2; ++b)
; #pragma unroll
;       for (int m = 0; m < 4; ++m)
; #pragma unroll
;         for (int n = 0; n < 2; ++n) acc[a][b][m][n] = (f32x4){0.f, 0.f, 0.f, 0.f};
;   bf16x8 At[4][2], B0[2][2], B1[2][2];
;   const char* cA = (const char*)g.A + (size_t)cur.pm * tstep; const char* cB = (const char*)g.Bt + (size_t)cur.pn * tstep;
;   PG8_STAGE(PG8_SB(0, 0), cB, voffB); PG8_STAGE(PG8_SA(0, 0), cA, voffA); PG8_STAGE(PG8_SB(0, 1), cB + hstep, voffB); PG8_STAGE(PG8_SA(0, 1), cA + hstep, voffA);
;   if (wr == 1) PG8_BAR;
.LBB0_362:
	v_mov_b32_e32 v14, v182
	s_waitcnt lgkmcnt(0)
	s_barrier
	s_and_b64 vcc, exec, s[2:3]
	v_readfirstlane_b32 s9, v14
	s_cbranch_vccnz .LBB0_502
	v_lshlrev_b32_e32 v0, 4, v14
	v_add_u32_e32 v1, 0x2000, v0
	v_ashrrev_i32_e32 v2, 31, v1
	v_lshrrev_b32_e32 v2, 22, v2
	v_add_u32_e32 v2, v1, v2
	v_ashrrev_i32_e32 v8, 10, v2
	v_mul_i32_i24_e32 v2, 0x400, v8
	v_sub_u32_e32 v1, v1, v2
	v_lshrrev_b32_e32 v2, 4, v1
	s_ashr_i32 s12, s9, 6
	v_bitop3_b32 v1, v2, v1, 32 bitop3:0x6c
	s_ashr_i32 s13, s9, 8
	s_lshl_b32 s34, s12, 10
	v_readlane_b32 s2, v237, 4
	v_ashrrev_i32_e32 v2, 31, v1
	s_add_u32 s35, s10, 0x1a3a8100
	v_readlane_b32 s3, v237, 5
	s_mul_i32 s24, s2, 0x300000
	v_lshrrev_b32_e32 v2, 26, v2
	s_addc_u32 s38, s11, 0
	s_lshl_b64 s[2:3], s[24:25], 1
	v_add_u32_e32 v2, v1, v2
	v_lshlrev_b32_e32 v3, 3, v8
	s_add_u32 s2, s10, s2
	v_ashrrev_i32_e32 v9, 6, v2
	v_and_b32_e32 v3, -16, v3
	s_addc_u32 s3, s11, s3
	v_add_u32_e32 v3, v9, v3
	s_add_u32 s24, s2, 0xf20000
	v_and_b32_e32 v4, 3, v9
	s_mov_b32 s2, 0x1fffe0
	v_lshrrev_b32_e32 v5, 2, v3
	v_lshlrev_b32_e32 v6, 1, v3
	v_and_b32_e32 v2, 0xc0, v2
	v_and_or_b32 v4, v3, s2, v4
	v_and_b32_e32 v5, 4, v5
	v_and_b32_e32 v6, 24, v6
	v_sub_u32_e32 v1, v1, v2
	v_or3_b32 v4, v4, v5, v6
	v_lshlrev_b32_e32 v5, 5, v8
	v_ashrrev_i16_sdwa v1, v188, sext(v1) dst_sel:DWORD dst_unused:UNUSED_PAD src0_sel:DWORD src1_sel:BYTE_0
	v_and_b32_e32 v5, 32, v5
	v_bfe_i32 v10, v1, 0, 16
	v_add_lshl_u32 v1, v5, v10, 1
	s_waitcnt vmcnt(0)
	v_lshl_add_u32 v132, v4, 11, v1
	v_lshl_add_u32 v134, v3, 11, v1
	v_bfe_i32 v1, v14, 27, 1
	v_lshrrev_b32_e32 v1, 22, v1
	v_add_u32_e32 v1, v0, v1
	v_and_b32_e32 v1, 0xfffffc00, v1
	v_sub_u32_e32 v0, v0, v1
	v_lshrrev_b32_e32 v1, 4, v0
	v_bitop3_b32 v1, v1, v0, 32 bitop3:0x6c
	v_ashrrev_i32_e32 v0, 31, v0
	v_lshrrev_b32_e32 v0, 26, v0
	v_add_u32_e32 v0, v1, v0
	v_ashrrev_i32_e32 v11, 6, v0
	v_ashrrev_i32_e32 v0, 31, v14
	v_lshrrev_b32_e32 v0, 26, v0
	v_add_u32_e32 v0, v14, v0
	v_ashrrev_i32_e32 v12, 6, v0
	v_lshlrev_b32_e32 v0, 3, v12
	v_and_b32_e32 v0, -16, v0
	v_add_u32_e32 v0, v11, v0
	v_and_b32_e32 v2, 3, v11
	s_addc_u32 s39, s3, 0
	v_and_or_b32 v2, v0, s2, v2
	v_readlane_b32 s2, v241, 50
	v_readlane_b32 s3, v241, 51
	s_mov_b32 s4, s2
	s_ashr_i32 s5, s2, 31
	v_writelane_b32 v241, s2, 50
	v_lshrrev_b32_e32 v3, 2, v0
	v_lshlrev_b32_e32 v4, 1, v0
	v_writelane_b32 v241, s3, 51
	v_and_b32_e32 v3, 4, v3
	v_and_b32_e32 v4, 24, v4
	s_lshl_b64 s[2:3], s[4:5], 19
	v_readlane_b32 s4, v241, 52
	v_or3_b32 v2, v2, v3, v4
	v_mul_i32_i24_e32 v4, 64, v11
	v_readlane_b32 s5, v241, 53
	v_sub_u32_e32 v1, v1, v4
	s_mov_b32 s14, s4
	s_ashr_i32 s15, s4, 31
	v_writelane_b32 v241, s4, 52
	v_lshlrev_b32_e32 v3, 5, v12
	v_ashrrev_i16_sdwa v1, v188, sext(v1) dst_sel:DWORD dst_unused:UNUSED_PAD src0_sel:DWORD src1_sel:BYTE_0
	v_writelane_b32 v241, s5, 53
	s_lshl_b64 s[4:5], s[14:15], 19
	v_and_b32_e32 v3, 32, v3
	v_bfe_i32 v13, v1, 0, 16
	s_add_u32 s4, s24, s4
	v_add_lshl_u32 v1, v3, v13, 1
	s_addc_u32 s5, s39, s5
	s_add_i32 s40, s34, 0
	v_lshl_add_u32 v136, v2, 11, v1
	s_add_i32 m0, s40, 0x10000
	v_lshl_add_u32 v138, v0, 11, v1
	global_load_lds_dwordx4 v136, s[4:5]
	s_add_i32 m0, s40, 0x12000
	s_add_u32 s2, s35, s2
	global_load_lds_dwordx4 v132, s[4:5]
	s_addc_u32 s3, s38, s3
	s_mov_b32 m0, s40
	s_add_i32 s41, s40, 0x2000
	global_load_lds_dwordx4 v138, s[2:3]
	s_mov_b32 m0, s41
	s_add_u32 s14, s4, 0x40000
	global_load_lds_dwordx4 v134, s[2:3]
	s_addc_u32 s15, s5, 0
	s_add_i32 m0, s40, 0x14000
	v_mov_b32_e32 v137, v145
	global_load_lds_dwordx4 v136, s[14:15]
	s_add_i32 m0, s40, 0x16000
	v_mov_b32_e32 v133, v145
	global_load_lds_dwordx4 v132, s[14:15]
	s_add_u32 s14, s2, 0x40000
	s_addc_u32 s15, s3, 0
	s_add_i32 s42, s40, 0x4000
	s_mov_b32 m0, s42
	s_add_i32 s43, s40, 0x6000
	global_load_lds_dwordx4 v138, s[14:15]
	s_mov_b32 m0, s43
	v_mov_b32_e32 v139, v145
	global_load_lds_dwordx4 v134, s[14:15]
	v_mov_b32_e32 v135, v145
	v_lshl_add_u64 v[6:7], s[4:5], 0, v[136:137]
	v_lshl_add_u64 v[4:5], s[4:5], 0, v[132:133]
	v_lshl_add_u64 v[2:3], s[2:3], 0, v[138:139]
	s_cmp_lg_u32 s13, 1
	v_lshl_add_u64 v[0:1], s[2:3], 0, v[134:135]
	s_cbranch_scc1 .LBB0_365
	s_barrier
	s_setprio 1

; #define PG8_WAIT_V(n) asm volatile("s_waitcnt vmcnt(" #n ")" ::: "memory")
; #define PG8_BAR __builtin_amdgcn_s_barrier()
; template <class Epi, class Sched>
; DI void gemm_phase(LAS unsigned char* lds, const Gemm g, const Sched& S, const Epi& E) {
;     ...
;   PG8_WAIT_V(0);
;   if (wr == 0) PG8_BAR;
;   PG8_BAR;
.LBB0_501:
	s_barrier
	s_setprio 0

; DI int get_tid() { int t = threadIdx.x; asm volatile("" : "+v"(t)); return t; }
; #define PG8_STAGE(bufoff, gbase, voff) do { _Pragma("unroll") for (int _i = 0; _i < 2; ++_i) \
;     __builtin_amdgcn_global_load_lds((const unsigned*)((const char*)(gbase) + (voff)[_i]), (LAS unsigned*)(lds + (bufoff) + ldsw + _i * 8192), 16, 0, 0); } while (0)
; #define PG8_BAR __builtin_amdgcn_s_barrier()
; template <class Epi, class Sched>
; DI void gemm_phase(LAS unsigned char* lds, const Gemm g, const Sched& S, const Epi& E) {
;   const int tid = get_tid(), wid = __builtin_amdgcn_readfirstlane(tid >> 6), lane = tid & 63, wr = wid >> 2, wc = wid & 3, fr = lane & 15, fq = lane >> 4;
;   const int K = g.K, nt = K / BK;
;   unsigned voffA[2], voffB[2];
; #pragma unroll
;   for (int i = 0; i < 2; ++i) { int R, C; stage_rc(tid * 16 + i * 8192, R, C); const int Rb = Epi::PERM ? ((R & ~31) + perm32(R & 31)) : R;
;     voffA[i] = (unsigned)(R * K + C) * 2u; voffB[i] = (unsigned)(Rb * K + C) * 2u; }
;   const size_t kstep = (size_t)(BK * 2);
;   const size_t hstep = (size_t)HALF * K * 2;
;   const size_t tstep = 2 * hstep;
;   const unsigned ldsw = (unsigned)wid * 1024u;
;   const int aoff = lds_byte(wr * 64 + fr, fq * 8), boff = lds_byte(wc * 32 + fr, fq * 8);
;     ...
;   Unit cur, nxt; int ui = 0;
;   if (!S.next(0, cur)) return;
;   f32x4 acc[2][2][4][2];
; #pragma unroll
;   for (int a = 0; a < 2; ++a)
; #pragma unroll
;     for (int b = 0; b < 2; ++b)
; #pragma unroll
;       for (int m = 0; m < 4; ++m)
; #pragma unroll
;         for (int n = 0; n < 2; ++n) acc[a][b][m][n] = (f32x4){0.f, 0.f, 0.f, 0.f};
;   bf16x8 At[4][2], B0[2][2], B1[2][2];
;   const char* cA = (const char*)g.A + (size_t)cur.pm * tstep; const char* cB = (const char*)g.Bt + (size_t)cur.pn * tstep;
;   PG8_STAGE(PG8_SB(0, 0), cB, voffB); PG8_STAGE(PG8_SA(0, 0), cA, voffA); PG8_STAGE(PG8_SB(0, 1), cB + hstep, voffB); PG8_STAGE(PG8_SA(0, 1), cA + hstep, voffA);
;   if (wr == 1) PG8_BAR;
.LBB0_681:
	v_mov_b32_e32 v8, v182
	s_waitcnt vmcnt(0) lgkmcnt(0)
	s_barrier
	s_and_b64 vcc, exec, s[2:3]
	v_readfirstlane_b32 s9, v8
	s_cbranch_vccnz .LBB0_1109
	v_lshlrev_b32_e32 v0, 4, v8
	v_add_u32_e32 v1, 0x2000, v0
	v_ashrrev_i32_e32 v2, 31, v1
	v_lshrrev_b32_e32 v2, 22, v2
	v_add_u32_e32 v2, v1, v2
	v_ashrrev_i32_e32 v9, 10, v2
	v_mul_i32_i24_e32 v2, 0x400, v9
	v_sub_u32_e32 v1, v1, v2
	v_lshrrev_b32_e32 v2, 4, v1
	v_bitop3_b32 v1, v2, v1, 32 bitop3:0x6c
	v_ashrrev_i32_e32 v2, 31, v1
	s_ashr_i32 s2, s9, 6
	v_lshrrev_b32_e32 v2, 26, v2
	s_ashr_i32 s3, s9, 8
	s_lshl_b32 s52, s2, 10
	v_readlane_b32 s4, v237, 4
	v_add_u32_e32 v2, v1, v2
	v_lshlrev_b32_e32 v3, 3, v9
	s_add_u32 s53, s10, 0x1a3a8100
	v_readlane_b32 s5, v237, 5
	s_mul_i32 s24, s4, 0x240000
	v_ashrrev_i32_e32 v10, 6, v2
	v_and_b32_e32 v3, -16, v3
	s_addc_u32 s54, s11, 0
	s_lshl_b64 s[4:5], s[24:25], 1
	v_add_u32_e32 v3, v10, v3
	s_add_u32 s24, s10, s4
	v_and_b32_e32 v4, 3, v10
	s_mov_b32 s4, 0x1fffe0
	v_lshrrev_b32_e32 v5, 2, v3
	v_lshlrev_b32_e32 v6, 1, v3
	v_and_b32_e32 v2, 0xc0, v2
	v_and_or_b32 v4, v3, s4, v4
	v_and_b32_e32 v5, 4, v5
	v_and_b32_e32 v6, 24, v6
	v_sub_u32_e32 v1, v1, v2
	v_or3_b32 v4, v4, v5, v6
	v_lshlrev_b32_e32 v5, 5, v9
	v_ashrrev_i16_sdwa v1, v188, sext(v1) dst_sel:DWORD dst_unused:UNUSED_PAD src0_sel:DWORD src1_sel:BYTE_0
	v_and_b32_e32 v5, 32, v5
	v_bfe_i32 v11, v1, 0, 16
	v_add_lshl_u32 v1, v5, v11, 1
	v_lshl_add_u32 v136, v4, 11, v1
	v_lshl_add_u32 v138, v3, 11, v1
	v_bfe_i32 v1, v8, 27, 1
	v_lshrrev_b32_e32 v1, 22, v1
	v_add_u32_e32 v1, v0, v1
	v_and_b32_e32 v1, 0xfffffc00, v1
	v_sub_u32_e32 v0, v0, v1
	v_lshrrev_b32_e32 v1, 4, v0
	v_bitop3_b32 v1, v1, v0, 32 bitop3:0x6c
	v_ashrrev_i32_e32 v0, 31, v0
	v_lshrrev_b32_e32 v0, 26, v0
	v_add_u32_e32 v0, v1, v0
	v_ashrrev_i32_e32 v12, 6, v0
	v_ashrrev_i32_e32 v0, 31, v8
	v_lshrrev_b32_e32 v0, 26, v0
	v_add_u32_e32 v0, v8, v0
	v_ashrrev_i32_e32 v13, 6, v0
	v_lshlrev_b32_e32 v0, 3, v13
	v_and_b32_e32 v0, -16, v0
	v_add_u32_e32 v0, v12, v0
	v_and_b32_e32 v2, 3, v12
	s_addc_u32 s55, s11, s5
	v_and_or_b32 v2, v0, s4, v2
	v_readlane_b32 s4, v240, 30
	v_readlane_b32 s5, v240, 31
	s_mov_b32 s6, s4
	s_ashr_i32 s7, s4, 31
	v_writelane_b32 v240, s4, 30
	v_lshrrev_b32_e32 v3, 2, v0
	v_lshlrev_b32_e32 v4, 1, v0
	v_writelane_b32 v240, s5, 31
	v_and_b32_e32 v3, 4, v3
	v_and_b32_e32 v4, 24, v4
	s_lshl_b64 s[4:5], s[6:7], 19
	v_readlane_b32 s6, v240, 32
	v_or3_b32 v2, v2, v3, v4
	v_mul_i32_i24_e32 v4, 64, v12
	v_readlane_b32 s7, v240, 33
	v_sub_u32_e32 v1, v1, v4
	s_mov_b32 s12, s6
	s_ashr_i32 s13, s6, 31
	v_writelane_b32 v240, s6, 32
	v_lshlrev_b32_e32 v3, 5, v13
	v_ashrrev_i16_sdwa v1, v188, sext(v1) dst_sel:DWORD dst_unused:UNUSED_PAD src0_sel:DWORD src1_sel:BYTE_0
	v_writelane_b32 v240, s7, 33
	s_lshl_b64 s[6:7], s[12:13], 19
	v_and_b32_e32 v3, 32, v3
	v_bfe_i32 v14, v1, 0, 16
	s_add_u32 s22, s24, s6
	v_add_lshl_u32 v1, v3, v14, 1
	s_addc_u32 s23, s55, s7
	s_add_i32 s56, s52, 0
	v_lshl_add_u32 v140, v2, 11, v1
	s_add_i32 m0, s56, 0x10000
	v_lshl_add_u32 v142, v0, 11, v1
	global_load_lds_dwordx4 v140, s[22:23]
	s_add_i32 m0, s56, 0x12000
	s_add_u32 s20, s53, s4
	global_load_lds_dwordx4 v136, s[22:23]
	s_addc_u32 s21, s54, s5
	s_mov_b32 m0, s56
	s_add_i32 s57, s56, 0x2000
	global_load_lds_dwordx4 v142, s[20:21]
	s_mov_b32 m0, s57
	s_add_u32 s4, s22, 0x40000
	global_load_lds_dwordx4 v138, s[20:21]
	s_addc_u32 s5, s23, 0
	s_add_i32 m0, s56, 0x14000
	v_mov_b32_e32 v141, v145
	global_load_lds_dwordx4 v140, s[4:5]
	s_add_i32 m0, s56, 0x16000
	v_mov_b32_e32 v137, v145
	global_load_lds_dwordx4 v136, s[4:5]
	s_add_u32 s4, s20, 0x40000
	s_addc_u32 s5, s21, 0
	s_add_i32 s58, s56, 0x4000
	s_mov_b32 m0, s58
	s_add_i32 s59, s56, 0x6000
	global_load_lds_dwordx4 v142, s[4:5]
	s_mov_b32 m0, s59
	v_mov_b32_e32 v143, v145
	global_load_lds_dwordx4 v138, s[4:5]
	v_mov_b32_e32 v139, v145
	v_lshl_add_u64 v[6:7], s[22:23], 0, v[140:141]
	v_lshl_add_u64 v[4:5], s[22:23], 0, v[136:137]
	v_lshl_add_u64 v[2:3], s[20:21], 0, v[142:143]
	s_cmp_lg_u32 s3, 1
	v_lshl_add_u64 v[0:1], s[20:21], 0, v[138:139]
	s_cbranch_scc1 .LBB0_684
	s_barrier
	s_setprio 1

; DI int get_tid() { int t = threadIdx.x; asm volatile("" : "+v"(t)); return t; }
; #define PG8_STAGE(bufoff, gbase, voff) do { _Pragma("unroll") for (int _i = 0; _i < 2; ++_i) \
;     __builtin_amdgcn_global_load_lds((const unsigned*)((const char*)(gbase) + (voff)[_i]), (LAS unsigned*)(lds + (bufoff) + ldsw + _i * 8192), 16, 0, 0); } while (0)
; #define PG8_BAR __builtin_amdgcn_s_barrier()
; template <class Epi, class Sched>
; DI void gemm_phase(LAS unsigned char* lds, const Gemm g, const Sched& S, const Epi& E) {
;   const int tid = get_tid(), wid = __builtin_amdgcn_readfirstlane(tid >> 6), lane = tid & 63, wr = wid >> 2, wc = wid & 3, fr = lane & 15, fq = lane >> 4;
;   const int K = g.K, nt = K / BK;
;   unsigned voffA[2], voffB[2];
; #pragma unroll
;   for (int i = 0; i < 2; ++i) { int R, C; stage_rc(tid * 16 + i * 8192, R, C); const int Rb = Epi::PERM ? ((R & ~31) + perm32(R & 31)) : R;
;     voffA[i] = (unsigned)(R * K + C) * 2u; voffB[i] = (unsigned)(Rb * K + C) * 2u; }
;   const size_t kstep = (size_t)(BK * 2);
;   const size_t hstep = (size_t)HALF * K * 2;
;   const size_t tstep = 2 * hstep;
;   const unsigned ldsw = (unsigned)wid * 1024u;
;   const int aoff = lds_byte(wr * 64 + fr, fq * 8), boff = lds_byte(wc * 32 + fr, fq * 8);
;     ...
;   Unit cur, nxt; int ui = 0;
;   if (!S.next(0, cur)) return;
;   f32x4 acc[2][2][4][2];
; #pragma unroll
;   for (int a = 0; a < 2; ++a)
; #pragma unroll
;     for (int b = 0; b < 2; ++b)
; #pragma unroll
;       for (int m = 0; m < 4; ++m)
; #pragma unroll
;         for (int n = 0; n < 2; ++n) acc[a][b][m][n] = (f32x4){0.f, 0.f, 0.f, 0.f};
;   bf16x8 At[4][2], B0[2][2], B1[2][2];
;   const char* cA = (const char*)g.A + (size_t)cur.pm * tstep; const char* cB = (const char*)g.Bt + (size_t)cur.pn * tstep;
;   PG8_STAGE(PG8_SB(0, 0), cB, voffB); PG8_STAGE(PG8_SA(0, 0), cA, voffA); PG8_STAGE(PG8_SB(0, 1), cB + hstep, voffB); PG8_STAGE(PG8_SA(0, 1), cA + hstep, voffA);
;   if (wr == 1) PG8_BAR;
.LBB0_1189:
	v_readlane_b32 s2, v241, 1
	v_readlane_b32 s3, v241, 2
	s_add_u32 s9, s2, s10
	s_addc_u32 s24, s3, s11
	v_readlane_b32 s2, v237, 4
	v_readlane_b32 s3, v237, 5
	s_add_u32 s6, s9, 0xa3a8100
	s_mov_b32 s3, s25
	s_addc_u32 s7, s24, 0
	s_and_b64 vcc, exec, s[76:77]
	v_writelane_b32 v237, s2, 4
	s_nop 1
	v_writelane_b32 v237, s3, 5
	s_cbranch_vccnz .LBB0_1301
	v_ashrrev_i32_e32 v1, 31, v16
	v_lshrrev_b32_e32 v1, 26, v1
	v_add_u32_e32 v1, v16, v1
	v_ashrrev_i32_e32 v8, 6, v1
	v_bfe_i32 v1, v16, 27, 1
	v_lshlrev_b32_e32 v0, 4, v16
	v_lshrrev_b32_e32 v1, 22, v1
	v_add_u32_e32 v1, v0, v1
	v_and_b32_e32 v1, 0xfffffc00, v1
	v_sub_u32_e32 v1, v0, v1
	v_lshrrev_b32_e32 v2, 4, v1
	v_bitop3_b32 v2, v2, v1, 32 bitop3:0x6c
	v_ashrrev_i32_e32 v1, 31, v1
	v_lshrrev_b32_e32 v1, 26, v1
	v_lshlrev_b32_e32 v3, 3, v8
	v_add_u32_e32 v1, v2, v1
	v_and_b32_e32 v3, -16, v3
	v_ashrrev_i32_e32 v10, 6, v1
	v_add_u32_e32 v1, v10, v3
	v_lshlrev_b32_e32 v3, 5, v8
	v_and_b32_e32 v9, 32, v3
	v_mul_i32_i24_e32 v3, 64, v10
	v_sub_u32_e32 v2, v2, v3
	v_ashrrev_i16_sdwa v2, v188, sext(v2) dst_sel:DWORD dst_unused:UNUSED_PAD src0_sel:DWORD src1_sel:BYTE_0
	v_lshlrev_b32_e32 v3, 1, v1
	v_lshrrev_b32_e32 v4, 2, v1
	v_and_b32_e32 v5, 3, v10
	s_mov_b32 s4, 0x1ffffe0
	v_bfe_i32 v11, v2, 0, 16
	v_and_b32_e32 v3, 24, v3
	v_and_b32_e32 v4, 4, v4
	v_and_or_b32 v5, v1, s4, v5
	s_movk_i32 s3, 0x180
	v_add_u32_e32 v2, v9, v11
	v_or3_b32 v3, v5, v4, v3
	v_mul_lo_u32 v1, v1, s3
	v_add_lshl_u32 v128, v2, v1, 1
	v_mul_lo_u32 v1, v3, s3
	v_add_u32_e32 v0, 0x2000, v0
	v_add_lshl_u32 v130, v1, v2, 1
	v_ashrrev_i32_e32 v1, 31, v0
	v_lshrrev_b32_e32 v1, 22, v1
	v_add_u32_e32 v1, v0, v1
	v_ashrrev_i32_e32 v12, 10, v1
	v_mul_i32_i24_e32 v1, 0x400, v12
	v_sub_u32_e32 v0, v0, v1
	v_lshrrev_b32_e32 v1, 4, v0
	v_bitop3_b32 v0, v1, v0, 32 bitop3:0x6c
	v_ashrrev_i32_e32 v2, 31, v0
	v_lshrrev_b32_e32 v2, 26, v2
	v_lshlrev_b32_e32 v1, 3, v12
	v_add_u32_e32 v2, v0, v2
	v_and_b32_e32 v1, -16, v1
	v_ashrrev_i32_e32 v14, 6, v2
	v_and_b32_e32 v2, 0xc0, v2
	v_add_u32_e32 v1, v14, v1
	v_lshlrev_b32_e32 v3, 5, v12
	v_sub_u32_e32 v0, v0, v2
	v_and_b32_e32 v13, 32, v3
	v_ashrrev_i16_sdwa v0, v188, sext(v0) dst_sel:DWORD dst_unused:UNUSED_PAD src0_sel:DWORD src1_sel:BYTE_0
	v_lshlrev_b32_e32 v2, 1, v1
	v_lshrrev_b32_e32 v3, 2, v1
	v_and_b32_e32 v4, 3, v14
	v_bfe_i32 v15, v0, 0, 16
	v_and_b32_e32 v2, 24, v2
	v_and_b32_e32 v3, 4, v3
	v_and_or_b32 v4, v1, s4, v4
	v_add_u32_e32 v0, v13, v15
	v_or3_b32 v2, v4, v3, v2
	v_mul_lo_u32 v1, v1, s3
	v_add_lshl_u32 v132, v0, v1, 1
	v_mul_lo_u32 v1, v2, s3
	s_ashr_i32 s3, s34, 6
	v_readlane_b32 s12, v237, 4
	s_ashr_i32 s2, s34, 8
	s_lshl_b32 s35, s3, 10
	s_mul_i32 s5, s12, 0x90000
	s_mul_hi_u32 s4, s12, 0x90000
	s_add_u32 s5, s9, s5
	s_addc_u32 s4, s24, s4
	v_readlane_b32 s13, v237, 5
	s_add_u32 s36, s5, 0x900000
	s_addc_u32 s37, s4, 0
	s_mul_i32 s13, s49, 0x30000
	s_mul_hi_i32 s12, s49, 0x30000
	s_add_u32 s20, s36, s13
	s_addc_u32 s21, s37, s12
	s_add_i32 s38, s35, 0
	s_add_i32 m0, s38, 0x10000
	s_mul_i32 s5, s50, 0x30000
	global_load_lds_dwordx4 v130, s[20:21]
	s_add_i32 m0, s38, 0x12000
	v_add_lshl_u32 v134, v1, v0, 1
	s_mul_hi_i32 s4, s50, 0x30000
	s_add_u32 s18, s6, s5
	global_load_lds_dwordx4 v134, s[20:21]
	s_addc_u32 s19, s7, s4
	s_mov_b32 m0, s38
	s_add_i32 s39, s38, 0x2000
	global_load_lds_dwordx4 v128, s[18:19]
	s_mov_b32 m0, s39
	s_add_u32 s4, s20, 0x18000
	global_load_lds_dwordx4 v132, s[18:19]
	s_addc_u32 s5, s21, 0
	s_add_i32 m0, s38, 0x14000
	v_mov_b32_e32 v131, v145
	global_load_lds_dwordx4 v130, s[4:5]
	s_add_i32 m0, s38, 0x16000
	v_mov_b32_e32 v135, v145
	global_load_lds_dwordx4 v134, s[4:5]
	s_add_u32 s4, s18, 0x18000
	s_addc_u32 s5, s19, 0
	s_add_i32 s40, s38, 0x4000
	s_mov_b32 m0, s40
	s_add_i32 s41, s38, 0x6000
	global_load_lds_dwordx4 v128, s[4:5]
	s_mov_b32 m0, s41
	v_mov_b32_e32 v129, v145
	global_load_lds_dwordx4 v132, s[4:5]
	v_mov_b32_e32 v133, v145
	v_lshl_add_u64 v[6:7], s[20:21], 0, v[130:131]
	v_lshl_add_u64 v[4:5], s[20:21], 0, v[134:135]
	v_lshl_add_u64 v[2:3], s[18:19], 0, v[128:129]
	s_cmp_lg_u32 s2, 1
	v_lshl_add_u64 v[0:1], s[18:19], 0, v[132:133]
	s_cbranch_scc1 .LBB0_1192
	s_barrier
	s_setprio 1

; DI int get_tid() { int t = threadIdx.x; asm volatile("" : "+v"(t)); return t; }
; #define PG8_STAGE(bufoff, gbase, voff) do { _Pragma("unroll") for (int _i = 0; _i < 2; ++_i) \
;     __builtin_amdgcn_global_load_lds((const unsigned*)((const char*)(gbase) + (voff)[_i]), (LAS unsigned*)(lds + (bufoff) + ldsw + _i * 8192), 16, 0, 0); } while (0)
; #define PG8_BAR __builtin_amdgcn_s_barrier()
; template <class Epi, class Sched>
; DI void gemm_phase(LAS unsigned char* lds, const Gemm g, const Sched& S, const Epi& E) {
;   const int tid = get_tid(), wid = __builtin_amdgcn_readfirstlane(tid >> 6), lane = tid & 63, wr = wid >> 2, wc = wid & 3, fr = lane & 15, fq = lane >> 4;
;   const int K = g.K, nt = K / BK;
;   unsigned voffA[2], voffB[2];
; #pragma unroll
;   for (int i = 0; i < 2; ++i) { int R, C; stage_rc(tid * 16 + i * 8192, R, C); const int Rb = Epi::PERM ? ((R & ~31) + perm32(R & 31)) : R;
;     voffA[i] = (unsigned)(R * K + C) * 2u; voffB[i] = (unsigned)(Rb * K + C) * 2u; }
;   const size_t kstep = (size_t)(BK * 2);
;   const size_t hstep = (size_t)HALF * K * 2;
;   const size_t tstep = 2 * hstep;
;   const unsigned ldsw = (unsigned)wid * 1024u;
;   const int aoff = lds_byte(wr * 64 + fr, fq * 8), boff = lds_byte(wc * 32 + fr, fq * 8);
;     ...
;   Unit cur, nxt; int ui = 0;
;   if (!S.next(0, cur)) return;
;   f32x4 acc[2][2][4][2];
; #pragma unroll
;   for (int a = 0; a < 2; ++a)
; #pragma unroll
;     for (int b = 0; b < 2; ++b)
; #pragma unroll
;       for (int m = 0; m < 4; ++m)
; #pragma unroll
;         for (int n = 0; n < 2; ++n) acc[a][b][m][n] = (f32x4){0.f, 0.f, 0.f, 0.f};
;   bf16x8 At[4][2], B0[2][2], B1[2][2];
;   const char* cA = (const char*)g.A + (size_t)cur.pm * tstep; const char* cB = (const char*)g.Bt + (size_t)cur.pn * tstep;
;   PG8_STAGE(PG8_SB(0, 0), cB, voffB); PG8_STAGE(PG8_SA(0, 0), cA, voffA); PG8_STAGE(PG8_SB(0, 1), cB + hstep, voffB); PG8_STAGE(PG8_SA(0, 1), cA + hstep, voffA);
;   if (wr == 1) PG8_BAR;
.LBB0_1334:
	s_and_b64 vcc, exec, s[76:77]
	s_cbranch_vccnz .LBB0_1414
	v_bfe_i32 v3, v0, 27, 1
	v_lshlrev_b32_e32 v1, 4, v0
	v_lshrrev_b32_e32 v3, 22, v3
	v_add_u32_e32 v3, v1, v3
	v_and_b32_e32 v3, 0xfffffc00, v3
	v_sub_u32_e32 v3, v1, v3
	v_ashrrev_i32_e32 v2, 31, v0
	v_lshrrev_b32_e32 v4, 4, v3
	v_lshrrev_b32_e32 v2, 26, v2
	v_bitop3_b32 v4, v4, v3, 32 bitop3:0x6c
	v_ashrrev_i32_e32 v3, 31, v3
	v_add_u32_e32 v2, v0, v2
	v_lshrrev_b32_e32 v3, 26, v3
	v_ashrrev_i32_e32 v2, 6, v2
	v_add_u32_e32 v3, v4, v3
	v_lshlrev_b32_e32 v5, 3, v2
	v_ashrrev_i32_e32 v3, 6, v3
	v_and_b32_e32 v5, -16, v5
	v_mul_i32_i24_e32 v6, 64, v3
	v_add_u32_e32 v5, v3, v5
	v_sub_u32_e32 v4, v4, v6
	v_lshlrev_b32_e32 v2, 5, v2
	v_ashrrev_i16_sdwa v4, v188, sext(v4) dst_sel:DWORD dst_unused:UNUSED_PAD src0_sel:DWORD src1_sel:BYTE_0
	v_lshlrev_b32_e32 v6, 1, v5
	v_lshrrev_b32_e32 v7, 2, v5
	v_and_b32_e32 v3, 3, v3
	s_mov_b32 s3, 0x7fffe0
	v_and_b32_e32 v2, 32, v2
	v_bfe_i32 v4, v4, 0, 16
	v_and_b32_e32 v6, 24, v6
	v_and_b32_e32 v7, 4, v7
	v_and_or_b32 v3, v5, s3, v3
	v_or3_b32 v3, v3, v7, v6
	v_add_lshl_u32 v2, v2, v4, 1
	v_add_u32_e32 v1, 0x2000, v1
	v_lshl_add_u32 v128, v5, 9, v2
	v_lshl_add_u32 v130, v3, 9, v2
	v_ashrrev_i32_e32 v2, 31, v1
	v_lshrrev_b32_e32 v2, 22, v2
	v_add_u32_e32 v2, v1, v2
	v_ashrrev_i32_e32 v2, 10, v2
	v_mul_i32_i24_e32 v3, 0x400, v2
	v_sub_u32_e32 v1, v1, v3
	v_lshrrev_b32_e32 v3, 4, v1
	v_bitop3_b32 v1, v3, v1, 32 bitop3:0x6c
	v_ashrrev_i32_e32 v4, 31, v1
	s_ashr_i32 s4, s50, 6
	v_lshrrev_b32_e32 v4, 26, v4
	v_lshlrev_b32_e32 v3, 3, v2
	v_add_u32_e32 v4, v1, v4
	s_ashr_i32 s5, s50, 8
	s_lshl_b32 s51, s4, 10
	v_readlane_b32 s10, v237, 4
	v_and_b32_e32 v3, -16, v3
	v_ashrrev_i32_e32 v5, 6, v4
	s_add_u32 s52, s9, 0xbba8100
	v_readlane_b32 s11, v237, 5
	v_add_u32_e32 v3, v5, v3
	v_and_b32_e32 v5, 3, v5
	s_addc_u32 s53, s24, 0
	s_lshl_b64 s[10:11], s[10:11], 19
	v_and_or_b32 v5, v3, s3, v5
	s_add_u32 s3, s9, s10
	s_addc_u32 s10, s24, s11
	s_add_u32 s54, s3, 0xa20000
	s_addc_u32 s55, s10, 0
	s_ashr_i32 s21, s20, 31
	s_ashr_i32 s3, s2, 31
	v_and_b32_e32 v4, 0xc0, v4
	s_lshl_b64 s[10:11], s[20:21], 17
	s_lshl_b64 s[12:13], s[2:3], 17
	v_sub_u32_e32 v1, v1, v4
	s_add_u32 s22, s54, s12
	v_lshlrev_b32_e32 v2, 5, v2
	v_ashrrev_i16_sdwa v1, v188, sext(v1) dst_sel:DWORD dst_unused:UNUSED_PAD src0_sel:DWORD src1_sel:BYTE_0
	v_lshlrev_b32_e32 v4, 1, v3
	v_lshrrev_b32_e32 v6, 2, v3
	s_addc_u32 s23, s55, s13
	s_add_i32 s56, s51, 0
	v_and_b32_e32 v2, 32, v2
	v_bfe_i32 v1, v1, 0, 16
	v_and_b32_e32 v4, 24, v4
	v_and_b32_e32 v6, 4, v6
	s_add_i32 m0, s56, 0x10000
	v_or3_b32 v4, v5, v6, v4
	v_add_lshl_u32 v1, v2, v1, 1
	global_load_lds_dwordx4 v130, s[22:23]
	s_add_i32 m0, s56, 0x12000
	v_lshl_add_u32 v134, v4, 9, v1
	s_add_u32 s28, s52, s10
	global_load_lds_dwordx4 v134, s[22:23]
	s_addc_u32 s29, s53, s11
	s_mov_b32 m0, s56
	s_add_i32 s57, s56, 0x2000
	v_lshl_add_u32 v132, v3, 9, v1
	global_load_lds_dwordx4 v128, s[28:29]
	s_mov_b32 m0, s57
	s_add_u32 s10, s22, 0x10000
	global_load_lds_dwordx4 v132, s[28:29]
	s_addc_u32 s11, s23, 0
	s_add_i32 m0, s56, 0x14000
	s_nop 0
	global_load_lds_dwordx4 v130, s[10:11]
	s_add_i32 m0, s56, 0x16000
	s_nop 0
	global_load_lds_dwordx4 v134, s[10:11]
	s_add_u32 s10, s28, 0x10000
	s_addc_u32 s11, s29, 0
	s_add_i32 s58, s56, 0x4000
	s_mov_b32 m0, s58
	s_add_i32 s59, s56, 0x6000
	global_load_lds_dwordx4 v128, s[10:11]
	s_mov_b32 m0, s59
	s_cmp_lg_u32 s5, 1
	global_load_lds_dwordx4 v132, s[10:11]
	s_cbranch_scc1 .LBB0_1337
	s_barrier
	s_setprio 1

; #define PG8_WAIT_V(n) asm volatile("s_waitcnt vmcnt(" #n ")" ::: "memory")
; #define PG8_BAR __builtin_amdgcn_s_barrier()
; template <class Epi, class Sched>
; DI void gemm_phase(LAS unsigned char* lds, const Gemm g, const Sched& S, const Epi& E) {
;     ...
;   PG8_WAIT_V(0);
;   if (wr == 0) PG8_BAR;
;   PG8_BAR;
.LBB0_1413:
	v_readlane_b32 s51, v237, 11
	s_barrier
	s_setprio 0

; DI int get_tid() { int t = threadIdx.x; asm volatile("" : "+v"(t)); return t; }
; #define PG8_STAGE(bufoff, gbase, voff) do { _Pragma("unroll") for (int _i = 0; _i < 2; ++_i) \
;     __builtin_amdgcn_global_load_lds((const unsigned*)((const char*)(gbase) + (voff)[_i]), (LAS unsigned*)(lds + (bufoff) + ldsw + _i * 8192), 16, 0, 0); } while (0)
; #define PG8_BAR __builtin_amdgcn_s_barrier()
; #define PH_BEGIN(n) if (ph_lo <= (n) && (n) < ph_hi) { LAUNDER(q); char* ws = q.ws; (void)ws;
; template <class Epi, class Sched>
; DI void gemm_phase(LAS unsigned char* lds, const Gemm g, const Sched& S, const Epi& E) {
;   const int tid = get_tid(), wid = __builtin_amdgcn_readfirstlane(tid >> 6), lane = tid & 63, wr = wid >> 2, wc = wid & 3, fr = lane & 15, fq = lane >> 4;
;   const int K = g.K, nt = K / BK;
;   unsigned voffA[2], voffB[2];
; #pragma unroll
;   for (int i = 0; i < 2; ++i) { int R, C; stage_rc(tid * 16 + i * 8192, R, C); const int Rb = Epi::PERM ? ((R & ~31) + perm32(R & 31)) : R;
;     voffA[i] = (unsigned)(R * K + C) * 2u; voffB[i] = (unsigned)(Rb * K + C) * 2u; }
;   const size_t kstep = (size_t)(BK * 2);
;   const size_t hstep = (size_t)HALF * K * 2;
;   const size_t tstep = 2 * hstep;
;   const unsigned ldsw = (unsigned)wid * 1024u;
;   const int aoff = lds_byte(wr * 64 + fr, fq * 8), boff = lds_byte(wc * 32 + fr, fq * 8);
;     ...
;   Unit cur, nxt; int ui = 0;
;   if (!S.next(0, cur)) return;
;   f32x4 acc[2][2][4][2];
; #pragma unroll
;   for (int a = 0; a < 2; ++a)
; #pragma unroll
;     for (int b = 0; b < 2; ++b)
; #pragma unroll
;       for (int m = 0; m < 4; ++m)
; #pragma unroll
;         for (int n = 0; n < 2; ++n) acc[a][b][m][n] = (f32x4){0.f, 0.f, 0.f, 0.f};
;   bf16x8 At[4][2], B0[2][2], B1[2][2];
;   const char* cA = (const char*)g.A + (size_t)cur.pm * tstep; const char* cB = (const char*)g.Bt + (size_t)cur.pn * tstep;
;   PG8_STAGE(PG8_SB(0, 0), cB, voffB); PG8_STAGE(PG8_SA(0, 0), cA, voffA); PG8_STAGE(PG8_SB(0, 1), cB + hstep, voffB); PG8_STAGE(PG8_SA(0, 1), cA + hstep, voffA);
;   if (wr == 1) PG8_BAR;
; __global__ void __launch_bounds__(512) mega(Params p, int ph_lo, int ph_hi) {
;     ...
;     PH_BEGIN(pb + 4)
;       run_gemm<EPI_RESID>(lds, (const u16*)(ws + B_H), (const u16*)(ws + (even ? W_ABOUT : W_COUT)) + (size_t)li * 1024 * 1024, 1024, 1024, q, (L == 0) ? q.x : nullptr, nullptr, (float*)(ws + TB_SSM));
.LBB0_1631:
	v_readlane_b32 s9, v237, 8
	s_or_b32 s4, s9, 5
	v_readlane_b32 s6, v241, 29
	v_readlane_b32 s7, v241, 30
	s_cmp_gt_i32 s6, s4
	s_cselect_b64 s[2:3], -1, 0
	s_cmp_ge_i32 s4, s7
	s_cselect_b64 s[4:5], -1, 0
	s_or_b64 s[2:3], s[2:3], s[4:5]
	s_and_b64 vcc, exec, s[2:3]
	v_readlane_b32 s2, v240, 36
	v_readlane_b32 s3, v240, 37
	s_nop 1
	v_cndmask_b32_e64 v0, 0, 1, s[2:3]
	v_cmp_ne_u32_e64 s[90:91], 1, v0
	s_cbranch_vccnz .LBB0_1790
	s_mov_b64 s[6:7], 0
	v_mov_b32_e32 v14, v182
	s_and_b64 vcc, exec, s[90:91]
	v_readfirstlane_b32 s9, v14
	s_cbranch_vccnz .LBB0_1736
	v_lshlrev_b32_e32 v0, 4, v14
	s_waitcnt lgkmcnt(0)
	v_add_u32_e32 v1, 0x2000, v0
	v_ashrrev_i32_e32 v2, 31, v1
	v_lshrrev_b32_e32 v2, 22, v2
	v_add_u32_e32 v2, v1, v2
	v_readlane_b32 s2, v241, 1
	v_ashrrev_i32_e32 v8, 10, v2
	v_readlane_b32 s3, v241, 2
	s_add_u32 s12, s2, s6
	v_mul_i32_i24_e32 v2, 0x400, v8
	s_addc_u32 s13, s3, s7
	v_sub_u32_e32 v1, v1, v2
	s_add_u32 s36, s12, 0x63a8100
	v_readlane_b32 s2, v237, 6
	v_lshrrev_b32_e32 v2, 4, v1
	s_addc_u32 s37, s13, 0
	v_readlane_b32 s3, v237, 7
	v_bitop3_b32 v1, v2, v1, 32 bitop3:0x6c
	s_and_b64 s[2:3], s[2:3], exec
	v_ashrrev_i32_e32 v2, 31, v1
	s_mov_b32 s2, 0xb20000
	v_lshrrev_b32_e32 v2, 26, v2
	s_cselect_b32 s2, s2, 0x1b20000
	v_add_u32_e32 v2, v1, v2
	v_lshlrev_b32_e32 v3, 3, v8
	s_add_u32 s2, s12, s2
	v_readlane_b32 s4, v237, 4
	v_ashrrev_i32_e32 v9, 6, v2
	v_and_b32_e32 v3, -16, v3
	s_addc_u32 s3, s13, 0
	s_lshl_b32 s4, s4, 21
	v_add_u32_e32 v3, v9, v3
	s_add_u32 s38, s2, s4
	v_and_b32_e32 v4, 3, v9
	s_mov_b32 s2, 0x1fffe0
	v_lshrrev_b32_e32 v5, 2, v3
	v_lshlrev_b32_e32 v6, 1, v3
	v_and_b32_e32 v2, 0xc0, v2
	v_and_or_b32 v4, v3, s2, v4
	v_and_b32_e32 v5, 4, v5
	v_and_b32_e32 v6, 24, v6
	v_sub_u32_e32 v1, v1, v2
	v_or3_b32 v4, v4, v5, v6
	v_lshlrev_b32_e32 v5, 5, v8
	v_ashrrev_i16_sdwa v1, v188, sext(v1) dst_sel:DWORD dst_unused:UNUSED_PAD src0_sel:DWORD src1_sel:BYTE_0
	v_and_b32_e32 v5, 32, v5
	v_bfe_i32 v10, v1, 0, 16
	v_add_lshl_u32 v1, v5, v10, 1
	s_waitcnt vmcnt(0)
	v_lshl_add_u32 v136, v4, 11, v1
	v_lshl_add_u32 v138, v3, 11, v1
	v_bfe_i32 v1, v14, 27, 1
	v_lshrrev_b32_e32 v1, 22, v1
	v_add_u32_e32 v1, v0, v1
	v_and_b32_e32 v1, 0xfffffc00, v1
	v_sub_u32_e32 v0, v0, v1
	v_lshrrev_b32_e32 v1, 4, v0
	v_bitop3_b32 v1, v1, v0, 32 bitop3:0x6c
	v_ashrrev_i32_e32 v0, 31, v0
	v_lshrrev_b32_e32 v0, 26, v0
	v_add_u32_e32 v0, v1, v0
	v_ashrrev_i32_e32 v11, 6, v0
	v_ashrrev_i32_e32 v0, 31, v14
	v_lshrrev_b32_e32 v0, 26, v0
	v_add_u32_e32 v0, v14, v0
	v_ashrrev_i32_e32 v12, 6, v0
	v_lshlrev_b32_e32 v0, 3, v12
	v_and_b32_e32 v0, -16, v0
	v_add_u32_e32 v0, v11, v0
	v_and_b32_e32 v2, 3, v11
	v_lshrrev_b32_e32 v3, 2, v0
	v_lshlrev_b32_e32 v4, 1, v0
	v_and_or_b32 v2, v0, s2, v2
	v_and_b32_e32 v3, 4, v3
	v_and_b32_e32 v4, 24, v4
	v_or3_b32 v2, v2, v3, v4
	v_mul_i32_i24_e32 v4, 64, v11
	s_addc_u32 s39, s3, 0
	s_ashr_i32 s15, s9, 6
	v_sub_u32_e32 v1, v1, v4
	s_ashr_i32 s14, s9, 8
	s_lshl_b32 s40, s15, 10
	v_lshlrev_b32_e32 v3, 5, v12
	v_ashrrev_i16_sdwa v1, v188, sext(v1) dst_sel:DWORD dst_unused:UNUSED_PAD src0_sel:DWORD src1_sel:BYTE_0
	v_readlane_b32 s2, v240, 47
	v_readlane_b32 s5, v237, 5
	v_and_b32_e32 v3, 32, v3
	v_bfe_i32 v13, v1, 0, 16
	v_readlane_b32 s3, v240, 48
	s_add_u32 s4, s38, s2
	v_add_lshl_u32 v1, v3, v13, 1
	s_addc_u32 s5, s39, s3
	s_add_i32 s41, s40, 0
	v_lshl_add_u32 v144, v2, 11, v1
	s_add_i32 m0, s41, 0x10000
	v_readlane_b32 s2, v240, 55
	global_load_lds_dwordx4 v144, s[4:5]
	s_add_i32 m0, s41, 0x12000
	v_readlane_b32 s3, v240, 56
	s_add_u32 s2, s36, s2
	v_lshl_add_u32 v140, v0, 11, v1
	global_load_lds_dwordx4 v136, s[4:5]
	s_addc_u32 s3, s37, s3
	s_mov_b32 m0, s41
	s_add_i32 s42, s41, 0x2000
	global_load_lds_dwordx4 v140, s[2:3]
	s_mov_b32 m0, s42
	s_add_u32 s10, s4, 0x40000
	global_load_lds_dwordx4 v138, s[2:3]
	s_addc_u32 s11, s5, 0
	s_add_i32 m0, s41, 0x14000
	v_mov_b32_e32 v137, v145
	global_load_lds_dwordx4 v144, s[10:11]
	s_add_i32 m0, s41, 0x16000
	v_mov_b32_e32 v141, v145
	global_load_lds_dwordx4 v136, s[10:11]
	s_add_u32 s10, s2, 0x40000
	s_addc_u32 s11, s3, 0
	s_add_i32 s43, s41, 0x4000
	s_mov_b32 m0, s43
	s_add_i32 s44, s41, 0x6000
	global_load_lds_dwordx4 v140, s[10:11]
	s_mov_b32 m0, s44
	v_mov_b32_e32 v139, v145
	global_load_lds_dwordx4 v138, s[10:11]
	v_lshl_add_u64 v[6:7], s[4:5], 0, v[144:145]
	v_lshl_add_u64 v[4:5], s[4:5], 0, v[136:137]
	v_lshl_add_u64 v[2:3], s[2:3], 0, v[140:141]
	s_cmp_lg_u32 s14, 1
	v_lshl_add_u64 v[0:1], s[2:3], 0, v[138:139]
	s_cbranch_scc1 .LBB0_1635
	s_barrier
	s_setprio 1

; DI int get_tid() { int t = threadIdx.x; asm volatile("" : "+v"(t)); return t; }
; #define PG8_STAGE(bufoff, gbase, voff) do { _Pragma("unroll") for (int _i = 0; _i < 2; ++_i) \
;     __builtin_amdgcn_global_load_lds((const unsigned*)((const char*)(gbase) + (voff)[_i]), (LAS unsigned*)(lds + (bufoff) + ldsw + _i * 8192), 16, 0, 0); } while (0)
; #define PG8_BAR __builtin_amdgcn_s_barrier()
; template <class Epi, class Sched>
; DI void gemm_phase(LAS unsigned char* lds, const Gemm g, const Sched& S, const Epi& E) {
;   const int tid = get_tid(), wid = __builtin_amdgcn_readfirstlane(tid >> 6), lane = tid & 63, wr = wid >> 2, wc = wid & 3, fr = lane & 15, fq = lane >> 4;
;   const int K = g.K, nt = K / BK;
;   unsigned voffA[2], voffB[2];
; #pragma unroll
;   for (int i = 0; i < 2; ++i) { int R, C; stage_rc(tid * 16 + i * 8192, R, C); const int Rb = Epi::PERM ? ((R & ~31) + perm32(R & 31)) : R;
;     voffA[i] = (unsigned)(R * K + C) * 2u; voffB[i] = (unsigned)(Rb * K + C) * 2u; }
;   const size_t kstep = (size_t)(BK * 2);
;   const size_t hstep = (size_t)HALF * K * 2;
;   const size_t tstep = 2 * hstep;
;   const unsigned ldsw = (unsigned)wid * 1024u;
;   const int aoff = lds_byte(wr * 64 + fr, fq * 8), boff = lds_byte(wc * 32 + fr, fq * 8);
;     ...
;   Unit cur, nxt; int ui = 0;
;   if (!S.next(0, cur)) return;
;   f32x4 acc[2][2][4][2];
; #pragma unroll
;   for (int a = 0; a < 2; ++a)
; #pragma unroll
;     for (int b = 0; b < 2; ++b)
; #pragma unroll
;       for (int m = 0; m < 4; ++m)
; #pragma unroll
;         for (int n = 0; n < 2; ++n) acc[a][b][m][n] = (f32x4){0.f, 0.f, 0.f, 0.f};
;   bf16x8 At[4][2], B0[2][2], B1[2][2];
;   const char* cA = (const char*)g.A + (size_t)cur.pm * tstep; const char* cB = (const char*)g.Bt + (size_t)cur.pn * tstep;
;   PG8_STAGE(PG8_SB(0, 0), cB, voffB); PG8_STAGE(PG8_SA(0, 0), cA, voffA); PG8_STAGE(PG8_SB(0, 1), cB + hstep, voffB); PG8_STAGE(PG8_SA(0, 1), cA + hstep, voffA);
;   if (wr == 1) PG8_BAR;
.LBB0_1818:
	v_mov_b32_e32 v14, v182
	s_waitcnt vmcnt(0) lgkmcnt(0)
	s_barrier
	s_and_b64 vcc, exec, s[2:3]
	v_readfirstlane_b32 s9, v14
	s_cbranch_vccnz .LBB0_1834
	v_lshlrev_b32_e32 v0, 4, v14
	v_add_u32_e32 v1, 0x2000, v0
	v_ashrrev_i32_e32 v2, 31, v1
	v_lshrrev_b32_e32 v2, 22, v2
	v_add_u32_e32 v2, v1, v2
	v_ashrrev_i32_e32 v8, 10, v2
	v_mul_i32_i24_e32 v2, 0x400, v8
	v_sub_u32_e32 v1, v1, v2
	v_lshrrev_b32_e32 v2, 4, v1
	s_ashr_i32 s2, s9, 6
	v_bitop3_b32 v1, v2, v1, 32 bitop3:0x6c
	s_ashr_i32 s3, s9, 8
	s_lshl_b32 s20, s2, 10
	v_ashrrev_i32_e32 v2, 31, v1
	s_add_u32 s21, s6, 0x1a3a8100
	v_lshrrev_b32_e32 v2, 26, v2
	s_addc_u32 s22, s7, 0
	s_lshl_b32 s4, s51, 23
	v_add_u32_e32 v2, v1, v2
	v_lshlrev_b32_e32 v3, 3, v8
	s_add_u32 s4, s6, s4
	v_ashrrev_i32_e32 v9, 6, v2
	v_and_b32_e32 v3, -16, v3
	s_addc_u32 s5, s7, 0
	v_add_u32_e32 v3, v9, v3
	s_add_u32 s23, s4, 0x1f20000
	v_and_b32_e32 v4, 3, v9
	s_mov_b32 s4, 0x1fffe0
	v_lshrrev_b32_e32 v5, 2, v3
	v_lshlrev_b32_e32 v6, 1, v3
	v_and_b32_e32 v2, 0xc0, v2
	v_and_or_b32 v4, v3, s4, v4
	v_and_b32_e32 v5, 4, v5
	v_and_b32_e32 v6, 24, v6
	v_sub_u32_e32 v1, v1, v2
	v_or3_b32 v4, v4, v5, v6
	v_lshlrev_b32_e32 v5, 5, v8
	v_ashrrev_i16_sdwa v1, v188, sext(v1) dst_sel:DWORD dst_unused:UNUSED_PAD src0_sel:DWORD src1_sel:BYTE_0
	v_and_b32_e32 v5, 32, v5
	v_bfe_i32 v10, v1, 0, 16
	v_add_lshl_u32 v1, v5, v10, 1
	v_lshl_add_u32 v128, v4, 11, v1
	v_lshl_add_u32 v130, v3, 11, v1
	v_bfe_i32 v1, v14, 27, 1
	v_lshrrev_b32_e32 v1, 22, v1
	v_add_u32_e32 v1, v0, v1
	v_and_b32_e32 v1, 0xfffffc00, v1
	v_sub_u32_e32 v0, v0, v1
	v_lshrrev_b32_e32 v1, 4, v0
	v_bitop3_b32 v1, v1, v0, 32 bitop3:0x6c
	v_ashrrev_i32_e32 v0, 31, v0
	v_lshrrev_b32_e32 v0, 26, v0
	v_add_u32_e32 v0, v1, v0
	v_ashrrev_i32_e32 v11, 6, v0
	v_ashrrev_i32_e32 v0, 31, v14
	v_lshrrev_b32_e32 v0, 26, v0
	v_add_u32_e32 v0, v14, v0
	v_ashrrev_i32_e32 v12, 6, v0
	v_lshlrev_b32_e32 v0, 3, v12
	v_and_b32_e32 v0, -16, v0
	v_add_u32_e32 v0, v11, v0
	v_and_b32_e32 v2, 3, v11
	v_lshrrev_b32_e32 v3, 2, v0
	v_lshlrev_b32_e32 v4, 1, v0
	v_and_or_b32 v2, v0, s4, v2
	v_and_b32_e32 v3, 4, v3
	v_and_b32_e32 v4, 24, v4
	v_or3_b32 v2, v2, v3, v4
	v_mul_i32_i24_e32 v4, 64, v11
	v_sub_u32_e32 v1, v1, v4
	s_addc_u32 s28, s5, 0
	v_lshlrev_b32_e32 v3, 5, v12
	v_ashrrev_i16_sdwa v1, v188, sext(v1) dst_sel:DWORD dst_unused:UNUSED_PAD src0_sel:DWORD src1_sel:BYTE_0
	v_readlane_b32 s4, v240, 44
	v_and_b32_e32 v3, 32, v3
	v_bfe_i32 v13, v1, 0, 16
	v_readlane_b32 s5, v240, 45
	s_add_u32 s16, s23, s4
	v_add_lshl_u32 v1, v3, v13, 1
	s_addc_u32 s17, s28, s5
	s_add_i32 s29, s20, 0
	v_lshl_add_u32 v132, v2, 11, v1
	s_add_i32 m0, s29, 0x10000
	v_readlane_b32 s4, v240, 51
	global_load_lds_dwordx4 v132, s[16:17]
	s_add_i32 m0, s29, 0x12000
	v_readlane_b32 s5, v240, 52
	s_add_u32 s14, s21, s4
	v_lshl_add_u32 v134, v0, 11, v1
	global_load_lds_dwordx4 v128, s[16:17]
	s_addc_u32 s15, s22, s5
	s_mov_b32 m0, s29
	s_add_i32 s34, s29, 0x2000
	global_load_lds_dwordx4 v134, s[14:15]
	s_mov_b32 m0, s34
	s_add_u32 s4, s16, 0x40000
	global_load_lds_dwordx4 v130, s[14:15]
	s_addc_u32 s5, s17, 0
	s_add_i32 m0, s29, 0x14000
	v_mov_b32_e32 v133, v145
	global_load_lds_dwordx4 v132, s[4:5]
	s_add_i32 m0, s29, 0x16000
	v_mov_b32_e32 v129, v145
	global_load_lds_dwordx4 v128, s[4:5]
	s_add_u32 s4, s14, 0x40000
	s_addc_u32 s5, s15, 0
	s_add_i32 s35, s29, 0x4000
	s_mov_b32 m0, s35
	s_add_i32 s38, s29, 0x6000
	global_load_lds_dwordx4 v134, s[4:5]
	s_mov_b32 m0, s38
	v_mov_b32_e32 v135, v145
	global_load_lds_dwordx4 v130, s[4:5]
	v_mov_b32_e32 v131, v145
	v_lshl_add_u64 v[6:7], s[16:17], 0, v[132:133]
	v_lshl_add_u64 v[4:5], s[16:17], 0, v[128:129]
	v_lshl_add_u64 v[2:3], s[14:15], 0, v[134:135]
	s_cmp_lg_u32 s3, 1
	v_lshl_add_u64 v[0:1], s[14:15], 0, v[130:131]
	s_cbranch_scc1 .LBB0_1821
	s_barrier
	s_setprio 1

; DI int get_tid() { int t = threadIdx.x; asm volatile("" : "+v"(t)); return t; }
; #define PG8_STAGE(bufoff, gbase, voff) do { _Pragma("unroll") for (int _i = 0; _i < 2; ++_i) \
;     __builtin_amdgcn_global_load_lds((const unsigned*)((const char*)(gbase) + (voff)[_i]), (LAS unsigned*)(lds + (bufoff) + ldsw + _i * 8192), 16, 0, 0); } while (0)
; #define PG8_BAR __builtin_amdgcn_s_barrier()
; template <class Epi, class Sched>
; DI void gemm_phase(LAS unsigned char* lds, const Gemm g, const Sched& S, const Epi& E) {
;   const int tid = get_tid(), wid = __builtin_amdgcn_readfirstlane(tid >> 6), lane = tid & 63, wr = wid >> 2, wc = wid & 3, fr = lane & 15, fq = lane >> 4;
;   const int K = g.K, nt = K / BK;
;   unsigned voffA[2], voffB[2];
; #pragma unroll
;   for (int i = 0; i < 2; ++i) { int R, C; stage_rc(tid * 16 + i * 8192, R, C); const int Rb = Epi::PERM ? ((R & ~31) + perm32(R & 31)) : R;
;     voffA[i] = (unsigned)(R * K + C) * 2u; voffB[i] = (unsigned)(Rb * K + C) * 2u; }
;   const size_t kstep = (size_t)(BK * 2);
;   const size_t hstep = (size_t)HALF * K * 2;
;   const size_t tstep = 2 * hstep;
;   const unsigned ldsw = (unsigned)wid * 1024u;
;   const int aoff = lds_byte(wr * 64 + fr, fq * 8), boff = lds_byte(wc * 32 + fr, fq * 8);
;     ...
;   Unit cur, nxt; int ui = 0;
;   if (!S.next(0, cur)) return;
;   f32x4 acc[2][2][4][2];
; #pragma unroll
;   for (int a = 0; a < 2; ++a)
; #pragma unroll
;     for (int b = 0; b < 2; ++b)
; #pragma unroll
;       for (int m = 0; m < 4; ++m)
; #pragma unroll
;         for (int n = 0; n < 2; ++n) acc[a][b][m][n] = (f32x4){0.f, 0.f, 0.f, 0.f};
;   bf16x8 At[4][2], B0[2][2], B1[2][2];
;   const char* cA = (const char*)g.A + (size_t)cur.pm * tstep; const char* cB = (const char*)g.Bt + (size_t)cur.pn * tstep;
;   PG8_STAGE(PG8_SB(0, 0), cB, voffB); PG8_STAGE(PG8_SA(0, 0), cA, voffA); PG8_STAGE(PG8_SB(0, 1), cB + hstep, voffB); PG8_STAGE(PG8_SA(0, 1), cA + hstep, voffA);
;   if (wr == 1) PG8_BAR;
.LBB0_1893:
	s_and_b64 vcc, exec, s[90:91]
	s_cbranch_vccnz .LBB0_1925
	s_waitcnt lgkmcnt(0)
	v_ashrrev_i32_e32 v1, 31, v8
	v_lshrrev_b32_e32 v1, 26, v1
	v_add_u32_e32 v1, v8, v1
	v_ashrrev_i32_e32 v9, 6, v1
	v_bfe_i32 v1, v8, 27, 1
	v_lshlrev_b32_e32 v0, 4, v8
	v_lshrrev_b32_e32 v1, 22, v1
	v_add_u32_e32 v1, v0, v1
	v_and_b32_e32 v1, 0xfffffc00, v1
	v_sub_u32_e32 v1, v0, v1
	v_lshrrev_b32_e32 v2, 4, v1
	v_bitop3_b32 v2, v2, v1, 32 bitop3:0x6c
	v_ashrrev_i32_e32 v1, 31, v1
	v_readlane_b32 s4, v241, 1
	v_lshrrev_b32_e32 v1, 26, v1
	v_readlane_b32 s5, v241, 2
	s_add_u32 s4, s4, s2
	v_add_u32_e32 v1, v2, v1
	s_addc_u32 s5, s5, s3
	v_ashrrev_i32_e32 v10, 6, v1
	s_add_u32 s34, s4, 0xa3a8100
	v_lshlrev_b32_e32 v3, 3, v9
	v_mul_i32_i24_e32 v4, 64, v10
	s_addc_u32 s35, s5, 0
	s_lshl_b32 s2, s51, 23
	v_and_b32_e32 v3, -16, v3
	v_sub_u32_e32 v2, v2, v4
	s_add_u32 s2, s4, s2
	v_add_u32_e32 v1, v10, v3
	v_lshlrev_b32_e32 v3, 5, v9
	v_ashrrev_i16_sdwa v2, v188, sext(v2) dst_sel:DWORD dst_unused:UNUSED_PAD src0_sel:DWORD src1_sel:BYTE_0
	s_addc_u32 s3, s5, 0
	v_and_b32_e32 v3, 32, v3
	v_bfe_i32 v11, v2, 0, 16
	s_add_u32 s36, s2, 0x3f20000
	v_and_b32_e32 v5, 3, v10
	s_mov_b32 s2, 0x7ffe0
	v_add_lshl_u32 v3, v3, v11, 1
	v_add_u32_e32 v0, 0x2000, v0
	v_lshlrev_b32_e32 v2, 1, v1
	v_lshrrev_b32_e32 v4, 2, v1
	v_and_or_b32 v5, v1, s2, v5
	s_waitcnt vmcnt(0)
	v_lshl_add_u32 v128, v1, 13, v3
	v_ashrrev_i32_e32 v1, 31, v0
	v_lshrrev_b32_e32 v1, 22, v1
	v_add_u32_e32 v1, v0, v1
	v_ashrrev_i32_e32 v12, 10, v1
	v_mul_i32_i24_e32 v1, 0x400, v12
	v_sub_u32_e32 v0, v0, v1
	v_and_b32_e32 v2, 24, v2
	v_and_b32_e32 v4, 4, v4
	v_lshrrev_b32_e32 v1, 4, v0
	v_or3_b32 v2, v5, v4, v2
	v_bitop3_b32 v0, v1, v0, 32 bitop3:0x6c
	v_lshl_add_u32 v144, v2, 13, v3
	v_ashrrev_i32_e32 v2, 31, v0
	v_lshrrev_b32_e32 v2, 26, v2
	v_lshlrev_b32_e32 v1, 3, v12
	v_add_u32_e32 v2, v0, v2
	v_and_b32_e32 v1, -16, v1
	v_ashrrev_i32_e32 v13, 6, v2
	s_addc_u32 s37, s3, 0
	v_add_u32_e32 v1, v13, v1
	v_and_b32_e32 v2, 0xc0, v2
	v_and_b32_e32 v4, 3, v13
	s_ashr_i32 s7, s9, 6
	s_ashr_i32 s19, s18, 31
	s_ashr_i32 s17, s16, 31
	s_ashr_i32 s6, s9, 8
	v_sub_u32_e32 v0, v0, v2
	v_and_or_b32 v4, v1, s2, v4
	s_lshl_b32 s38, s7, 10
	s_lshl_b64 s[2:3], s[18:19], 21
	s_lshl_b64 s[10:11], s[16:17], 21
	v_ashrrev_i16_sdwa v0, v188, sext(v0) dst_sel:DWORD dst_unused:UNUSED_PAD src0_sel:DWORD src1_sel:BYTE_0
	s_add_u32 s22, s36, s10
	v_lshlrev_b32_e32 v3, 5, v12
	v_bfe_i32 v14, v0, 0, 16
	v_lshlrev_b32_e32 v0, 1, v1
	v_lshrrev_b32_e32 v2, 2, v1
	s_addc_u32 s23, s37, s11
	s_add_i32 s39, s38, 0
	v_and_b32_e32 v3, 32, v3
	v_and_b32_e32 v0, 24, v0
	v_and_b32_e32 v2, 4, v2
	s_add_i32 m0, s39, 0x10000
	v_or3_b32 v0, v4, v2, v0
	v_add_lshl_u32 v2, v3, v14, 1
	global_load_lds_dwordx4 v144, s[22:23]
	s_add_i32 m0, s39, 0x12000
	v_lshl_add_u32 v132, v0, 13, v2
	s_add_u32 s20, s34, s2
	global_load_lds_dwordx4 v132, s[22:23]
	s_addc_u32 s21, s35, s3
	s_mov_b32 m0, s39
	s_add_i32 s40, s39, 0x2000
	v_lshl_add_u32 v130, v1, 13, v2
	global_load_lds_dwordx4 v128, s[20:21]
	s_mov_b32 m0, s40
	s_add_u32 s2, s22, 0x100000
	global_load_lds_dwordx4 v130, s[20:21]
	s_addc_u32 s3, s23, 0
	s_add_i32 m0, s39, 0x14000
	v_mov_b32_e32 v133, v145
	global_load_lds_dwordx4 v144, s[2:3]
	s_add_i32 m0, s39, 0x16000
	v_mov_b32_e32 v129, v145
	global_load_lds_dwordx4 v132, s[2:3]
	s_add_u32 s2, s20, 0x100000
	s_addc_u32 s3, s21, 0
	s_add_i32 s41, s39, 0x4000
	s_mov_b32 m0, s41
	s_add_i32 s42, s39, 0x6000
	global_load_lds_dwordx4 v128, s[2:3]
	s_mov_b32 m0, s42
	v_mov_b32_e32 v131, v145
	global_load_lds_dwordx4 v130, s[2:3]
	v_lshl_add_u64 v[6:7], s[22:23], 0, v[144:145]
	v_lshl_add_u64 v[4:5], s[22:23], 0, v[132:133]
	v_lshl_add_u64 v[2:3], s[20:21], 0, v[128:129]
	s_cmp_lg_u32 s6, 1
	v_lshl_add_u64 v[0:1], s[20:21], 0, v[130:131]
	s_cbranch_scc1 .LBB0_1896
	s_barrier
	s_setprio 1
